# SGU in-projection epilogue (u*silu(gate) tiles): arithmetic re-emitted two elements at a time, no s_nop pads, plain v_mul scaling
# speedup vs baseline: 1.0049x; 1.0034x over previous
.LBB0_375:
	v_ashrrev_i32_e32 v135, 31, v134
	v_lshl_add_u64 v[138:139], v[134:135], 2, s[86:87]
	global_load_dword v0, v[138:139], off
	v_lshl_or_b32 v136, s19, 7, v149
	v_readlane_b32 s26, v252, 17
	v_ashrrev_i32_e32 v137, 31, v136
	v_readlane_b32 s27, v252, 18
	s_waitcnt vmcnt(0)
	v_mul_f32_e32 v130, v0, v126
	v_mul_f32_e32 v131, v0, v118
	v_mul_f32_e32 v200, v0, v122
	v_mul_f32_e32 v201, v0, v114
	v_mul_f32_e32 v130, v130, v131
	v_mul_f32_e32 v131, 0xbfb8aa3b, v131
	v_mul_f32_e32 v200, v200, v201
	v_mul_f32_e32 v201, 0xbfb8aa3b, v201
	v_exp_f32_e32 v131, v131
	v_exp_f32_e32 v201, v201
	v_add_f32_e32 v131, 1.0, v131
	v_add_f32_e32 v201, 1.0, v201
	v_rcp_f32_e32 v131, v131
	v_rcp_f32_e32 v201, v201
	v_mul_f32_e32 v132, v130, v131
	v_mul_f32_e32 v133, v200, v201
	v_mul_f32_e32 v130, v0, v127
	v_mul_f32_e32 v131, v0, v119
	v_mul_f32_e32 v200, v0, v123
	v_mul_f32_e32 v201, v0, v115
	v_mul_f32_e32 v130, v130, v131
	v_mul_f32_e32 v131, 0xbfb8aa3b, v131
	v_mul_f32_e32 v200, v200, v201
	v_mul_f32_e32 v201, 0xbfb8aa3b, v201
	v_exp_f32_e32 v131, v131
	v_exp_f32_e32 v201, v201
	v_add_f32_e32 v131, 1.0, v131
	v_add_f32_e32 v201, 1.0, v201
	v_rcp_f32_e32 v131, v131
	v_rcp_f32_e32 v201, v201
	v_mul_f32_e32 v140, v130, v131
	v_mul_f32_e32 v141, v200, v201
	v_mul_f32_e32 v130, v0, v128
	v_mul_f32_e32 v131, v0, v120
	v_mul_f32_e32 v200, v0, v124
	v_mul_f32_e32 v201, v0, v116
	v_mul_f32_e32 v130, v130, v131
	v_mul_f32_e32 v131, 0xbfb8aa3b, v131
	v_mul_f32_e32 v200, v200, v201
	v_mul_f32_e32 v201, 0xbfb8aa3b, v201
	v_exp_f32_e32 v131, v131
	v_exp_f32_e32 v201, v201
	v_add_f32_e32 v131, 1.0, v131
	v_add_f32_e32 v201, 1.0, v201
	v_rcp_f32_e32 v131, v131
	v_rcp_f32_e32 v201, v201
	v_mul_f32_e32 v142, v130, v131
	v_mul_f32_e32 v143, v200, v201
	v_mul_f32_e32 v130, v0, v129
	v_mul_f32_e32 v131, v0, v121
	v_mul_f32_e32 v200, v0, v125
	v_mul_f32_e32 v201, v0, v117
	v_mul_f32_e32 v130, v130, v131
	v_mul_f32_e32 v131, 0xbfb8aa3b, v131
	v_mul_f32_e32 v200, v200, v201
	v_mul_f32_e32 v201, 0xbfb8aa3b, v201
	v_exp_f32_e32 v131, v131
	v_exp_f32_e32 v201, v201
	v_add_f32_e32 v131, 1.0, v131
	v_add_f32_e32 v201, 1.0, v201
	v_rcp_f32_e32 v131, v131
	v_rcp_f32_e32 v201, v201
	v_mul_f32_e32 v152, v130, v131
	v_mul_f32_e32 v0, v200, v201
	v_cvt_pk_bf16_f32 v130, v132, v140
	v_cvt_pk_bf16_f32 v131, v142, v152
	v_cvt_pk_bf16_f32 v132, v133, v141
	v_lshlrev_b64 v[140:141], 12, v[134:135]
	v_cvt_pk_bf16_f32 v133, v143, v0
	v_lshl_add_u64 v[142:143], s[26:27], 0, v[140:141]
	v_lshlrev_b64 v[140:141], 1, v[136:137]
	v_lshl_add_u64 v[136:137], v[142:143], 0, v[140:141]
	global_store_dwordx4 v[136:137], v[130:133], off
	global_load_dword v0, v[138:139], off offset:64
	v_or_b32_e32 v142, 16, v134
	v_ashrrev_i32_e32 v143, 31, v142
	v_lshlrev_b64 v[142:143], 12, v[142:143]
	v_lshl_add_u64 v[142:143], s[26:27], 0, v[142:143]
	v_lshl_add_u64 v[142:143], v[142:143], 0, v[140:141]
	s_waitcnt vmcnt(0)
	v_mul_f32_e32 v130, v0, v110
	v_mul_f32_e32 v131, v0, v102
	v_mul_f32_e32 v200, v0, v106
	v_mul_f32_e32 v201, v0, v98
	v_mul_f32_e32 v130, v130, v131
	v_mul_f32_e32 v131, 0xbfb8aa3b, v131
	v_mul_f32_e32 v200, v200, v201
	v_mul_f32_e32 v201, 0xbfb8aa3b, v201
	v_exp_f32_e32 v131, v131
	v_exp_f32_e32 v201, v201
	v_add_f32_e32 v131, 1.0, v131
	v_add_f32_e32 v201, 1.0, v201
	v_rcp_f32_e32 v131, v131
	v_rcp_f32_e32 v201, v201
	v_mul_f32_e32 v132, v130, v131
	v_mul_f32_e32 v133, v200, v201
	v_mul_f32_e32 v130, v0, v111
	v_mul_f32_e32 v131, v0, v103
	v_mul_f32_e32 v200, v0, v107
	v_mul_f32_e32 v201, v0, v99
	v_mul_f32_e32 v130, v130, v131
	v_mul_f32_e32 v131, 0xbfb8aa3b, v131
	v_mul_f32_e32 v200, v200, v201
	v_mul_f32_e32 v201, 0xbfb8aa3b, v201
	v_exp_f32_e32 v131, v131
	v_exp_f32_e32 v201, v201
	v_add_f32_e32 v131, 1.0, v131
	v_add_f32_e32 v201, 1.0, v201
	v_rcp_f32_e32 v131, v131
	v_rcp_f32_e32 v201, v201
	v_mul_f32_e32 v135, v130, v131
	v_mul_f32_e32 v152, v200, v201
	v_mul_f32_e32 v130, v0, v112
	v_mul_f32_e32 v131, v0, v104
	v_mul_f32_e32 v200, v0, v108
	v_mul_f32_e32 v201, v0, v100
	v_mul_f32_e32 v130, v130, v131
	v_mul_f32_e32 v131, 0xbfb8aa3b, v131
	v_mul_f32_e32 v200, v200, v201
	v_mul_f32_e32 v201, 0xbfb8aa3b, v201
	v_exp_f32_e32 v131, v131
	v_exp_f32_e32 v201, v201
	v_add_f32_e32 v131, 1.0, v131
	v_add_f32_e32 v201, 1.0, v201
	v_rcp_f32_e32 v131, v131
	v_rcp_f32_e32 v201, v201
	v_mul_f32_e32 v153, v130, v131
	v_mul_f32_e32 v154, v200, v201
	v_mul_f32_e32 v130, v0, v113
	v_mul_f32_e32 v131, v0, v105
	v_mul_f32_e32 v200, v0, v109
	v_mul_f32_e32 v201, v0, v101
	v_mul_f32_e32 v130, v130, v131
	v_mul_f32_e32 v131, 0xbfb8aa3b, v131
	v_mul_f32_e32 v200, v200, v201
	v_mul_f32_e32 v201, 0xbfb8aa3b, v201
	v_exp_f32_e32 v131, v131
	v_exp_f32_e32 v201, v201
	v_add_f32_e32 v131, 1.0, v131
	v_add_f32_e32 v201, 1.0, v201
	v_rcp_f32_e32 v131, v131
	v_rcp_f32_e32 v201, v201
	v_mul_f32_e32 v155, v130, v131
	v_mul_f32_e32 v0, v200, v201
	v_cvt_pk_bf16_f32 v130, v132, v135
	v_cvt_pk_bf16_f32 v131, v153, v155
	v_cvt_pk_bf16_f32 v132, v133, v152
	v_cvt_pk_bf16_f32 v133, v154, v0
	global_store_dwordx4 v[142:143], v[130:133], off
	global_load_dword v0, v[138:139], off offset:128
	v_or_b32_e32 v142, 32, v134
	v_ashrrev_i32_e32 v143, 31, v142
	v_lshlrev_b64 v[142:143], 12, v[142:143]
	v_lshl_add_u64 v[142:143], s[26:27], 0, v[142:143]
	v_lshl_add_u64 v[142:143], v[142:143], 0, v[140:141]
	s_waitcnt vmcnt(0)
	v_mul_f32_e32 v130, v0, v94
	v_mul_f32_e32 v131, v0, v86
	v_mul_f32_e32 v200, v0, v90
	v_mul_f32_e32 v201, v0, v82
	v_mul_f32_e32 v130, v130, v131
	v_mul_f32_e32 v131, 0xbfb8aa3b, v131
	v_mul_f32_e32 v200, v200, v201
	v_mul_f32_e32 v201, 0xbfb8aa3b, v201
	v_exp_f32_e32 v131, v131
	v_exp_f32_e32 v201, v201
	v_add_f32_e32 v131, 1.0, v131
	v_add_f32_e32 v201, 1.0, v201
	v_rcp_f32_e32 v131, v131
	v_rcp_f32_e32 v201, v201
	v_mul_f32_e32 v132, v130, v131
	v_mul_f32_e32 v133, v200, v201
	v_mul_f32_e32 v130, v0, v95
	v_mul_f32_e32 v131, v0, v87
	v_mul_f32_e32 v200, v0, v91
	v_mul_f32_e32 v201, v0, v83
	v_mul_f32_e32 v130, v130, v131
	v_mul_f32_e32 v131, 0xbfb8aa3b, v131
	v_mul_f32_e32 v200, v200, v201
	v_mul_f32_e32 v201, 0xbfb8aa3b, v201
	v_exp_f32_e32 v131, v131
	v_exp_f32_e32 v201, v201
	v_add_f32_e32 v131, 1.0, v131
	v_add_f32_e32 v201, 1.0, v201
	v_rcp_f32_e32 v131, v131
	v_rcp_f32_e32 v201, v201
	v_mul_f32_e32 v135, v130, v131
	v_mul_f32_e32 v152, v200, v201
	v_mul_f32_e32 v130, v0, v96
	v_mul_f32_e32 v131, v0, v88
	v_mul_f32_e32 v200, v0, v92
	v_mul_f32_e32 v201, v0, v84
	v_mul_f32_e32 v130, v130, v131
	v_mul_f32_e32 v131, 0xbfb8aa3b, v131
	v_mul_f32_e32 v200, v200, v201
	v_mul_f32_e32 v201, 0xbfb8aa3b, v201
	v_exp_f32_e32 v131, v131
	v_exp_f32_e32 v201, v201
	v_add_f32_e32 v131, 1.0, v131
	v_add_f32_e32 v201, 1.0, v201
	v_rcp_f32_e32 v131, v131
	v_rcp_f32_e32 v201, v201
	v_mul_f32_e32 v153, v130, v131
	v_mul_f32_e32 v154, v200, v201
	v_mul_f32_e32 v130, v0, v97
	v_mul_f32_e32 v131, v0, v89
	v_mul_f32_e32 v200, v0, v93
	v_mul_f32_e32 v201, v0, v85
	v_mul_f32_e32 v130, v130, v131
	v_mul_f32_e32 v131, 0xbfb8aa3b, v131
	v_mul_f32_e32 v200, v200, v201
	v_mul_f32_e32 v201, 0xbfb8aa3b, v201
	v_exp_f32_e32 v131, v131
	v_exp_f32_e32 v201, v201
	v_add_f32_e32 v131, 1.0, v131
	v_add_f32_e32 v201, 1.0, v201
	v_rcp_f32_e32 v131, v131
	v_rcp_f32_e32 v201, v201
	v_mul_f32_e32 v155, v130, v131
	v_mul_f32_e32 v0, v200, v201
	v_cvt_pk_bf16_f32 v130, v132, v135
	v_cvt_pk_bf16_f32 v131, v153, v155
	v_cvt_pk_bf16_f32 v132, v133, v152
	v_cvt_pk_bf16_f32 v133, v154, v0
	global_store_dwordx4 v[142:143], v[130:133], off
	global_load_dword v0, v[138:139], off offset:192
	v_or_b32_e32 v142, 48, v134
	v_ashrrev_i32_e32 v143, 31, v142
	v_lshlrev_b64 v[142:143], 12, v[142:143]
	v_lshl_add_u64 v[142:143], s[26:27], 0, v[142:143]
	v_lshl_add_u64 v[140:141], v[142:143], 0, v[140:141]
	s_mov_b32 s26, 0x80000
	s_waitcnt vmcnt(0)
	v_mul_f32_e32 v130, v0, v78
	v_mul_f32_e32 v131, v0, v70
	v_mul_f32_e32 v200, v0, v74
	v_mul_f32_e32 v201, v0, v66
	v_mul_f32_e32 v130, v130, v131
	v_mul_f32_e32 v131, 0xbfb8aa3b, v131
	v_mul_f32_e32 v200, v200, v201
	v_mul_f32_e32 v201, 0xbfb8aa3b, v201
	v_exp_f32_e32 v131, v131
	v_exp_f32_e32 v201, v201
	v_add_f32_e32 v131, 1.0, v131
	v_add_f32_e32 v201, 1.0, v201
	v_rcp_f32_e32 v131, v131
	v_rcp_f32_e32 v201, v201
	v_mul_f32_e32 v132, v130, v131
	v_mul_f32_e32 v133, v200, v201
	v_mul_f32_e32 v130, v0, v79
	v_mul_f32_e32 v131, v0, v71
	v_mul_f32_e32 v200, v0, v75
	v_mul_f32_e32 v201, v0, v67
	v_mul_f32_e32 v130, v130, v131
	v_mul_f32_e32 v131, 0xbfb8aa3b, v131
	v_mul_f32_e32 v200, v200, v201
	v_mul_f32_e32 v201, 0xbfb8aa3b, v201
	v_exp_f32_e32 v131, v131
	v_exp_f32_e32 v201, v201
	v_add_f32_e32 v131, 1.0, v131
	v_add_f32_e32 v201, 1.0, v201
	v_rcp_f32_e32 v131, v131
	v_rcp_f32_e32 v201, v201
	v_mul_f32_e32 v135, v130, v131
	v_mul_f32_e32 v152, v200, v201
	v_mul_f32_e32 v130, v0, v80
	v_mul_f32_e32 v131, v0, v72
	v_mul_f32_e32 v200, v0, v76
	v_mul_f32_e32 v201, v0, v68
	v_mul_f32_e32 v130, v130, v131
	v_mul_f32_e32 v131, 0xbfb8aa3b, v131
	v_mul_f32_e32 v200, v200, v201
	v_mul_f32_e32 v201, 0xbfb8aa3b, v201
	v_exp_f32_e32 v131, v131
	v_exp_f32_e32 v201, v201
	v_add_f32_e32 v131, 1.0, v131
	v_add_f32_e32 v201, 1.0, v201
	v_rcp_f32_e32 v131, v131
	v_rcp_f32_e32 v201, v201
	v_mul_f32_e32 v153, v130, v131
	v_mul_f32_e32 v154, v200, v201
	v_mul_f32_e32 v130, v0, v81
	v_mul_f32_e32 v131, v0, v73
	v_mul_f32_e32 v200, v0, v77
	v_mul_f32_e32 v201, v0, v69
	v_mul_f32_e32 v130, v130, v131
	v_mul_f32_e32 v131, 0xbfb8aa3b, v131
	v_mul_f32_e32 v200, v200, v201
	v_mul_f32_e32 v201, 0xbfb8aa3b, v201
	v_exp_f32_e32 v131, v131
	v_exp_f32_e32 v201, v201
	v_add_f32_e32 v131, 1.0, v131
	v_add_f32_e32 v201, 1.0, v201
	v_rcp_f32_e32 v131, v131
	v_rcp_f32_e32 v201, v201
	v_mul_f32_e32 v155, v130, v131
	v_mul_f32_e32 v0, v200, v201
	v_cvt_pk_bf16_f32 v130, v132, v135
	v_cvt_pk_bf16_f32 v131, v153, v155
	v_cvt_pk_bf16_f32 v132, v133, v152
	v_cvt_pk_bf16_f32 v133, v154, v0
	global_store_dwordx4 v[140:141], v[130:133], off
	global_load_dword v0, v[138:139], off offset:512
	s_nop 0
	s_waitcnt vmcnt(0)
	v_mul_f32_e32 v130, v0, v62
	v_mul_f32_e32 v131, v0, v54
	v_mul_f32_e32 v200, v0, v58
	v_mul_f32_e32 v201, v0, v50
	v_mul_f32_e32 v130, v130, v131
	v_mul_f32_e32 v131, 0xbfb8aa3b, v131
	v_mul_f32_e32 v200, v200, v201
	v_mul_f32_e32 v201, 0xbfb8aa3b, v201
	v_exp_f32_e32 v131, v131
	v_exp_f32_e32 v201, v201
	v_add_f32_e32 v131, 1.0, v131
	v_add_f32_e32 v201, 1.0, v201
	v_rcp_f32_e32 v131, v131
	v_rcp_f32_e32 v201, v201
	v_mul_f32_e32 v132, v130, v131
	v_mul_f32_e32 v133, v200, v201
	v_mul_f32_e32 v130, v0, v63
	v_mul_f32_e32 v131, v0, v55
	v_mul_f32_e32 v200, v0, v59
	v_mul_f32_e32 v201, v0, v51
	v_mul_f32_e32 v130, v130, v131
	v_mul_f32_e32 v131, 0xbfb8aa3b, v131
	v_mul_f32_e32 v200, v200, v201
	v_mul_f32_e32 v201, 0xbfb8aa3b, v201
	v_exp_f32_e32 v131, v131
	v_exp_f32_e32 v201, v201
	v_add_f32_e32 v131, 1.0, v131
	v_add_f32_e32 v201, 1.0, v201
	v_rcp_f32_e32 v131, v131
	v_rcp_f32_e32 v201, v201
	v_mul_f32_e32 v135, v130, v131
	v_mul_f32_e32 v140, v200, v201
	v_mul_f32_e32 v130, v0, v64
	v_mul_f32_e32 v131, v0, v56
	v_mul_f32_e32 v200, v0, v60
	v_mul_f32_e32 v201, v0, v52
	v_mul_f32_e32 v130, v130, v131
	v_mul_f32_e32 v131, 0xbfb8aa3b, v131
	v_mul_f32_e32 v200, v200, v201
	v_mul_f32_e32 v201, 0xbfb8aa3b, v201
	v_exp_f32_e32 v131, v131
	v_exp_f32_e32 v201, v201
	v_add_f32_e32 v131, 1.0, v131
	v_add_f32_e32 v201, 1.0, v201
	v_rcp_f32_e32 v131, v131
	v_rcp_f32_e32 v201, v201
	v_mul_f32_e32 v141, v130, v131
	v_mul_f32_e32 v142, v200, v201
	v_mul_f32_e32 v130, v0, v65
	v_mul_f32_e32 v131, v0, v57
	v_mul_f32_e32 v200, v0, v61
	v_mul_f32_e32 v201, v0, v53
	v_mul_f32_e32 v130, v130, v131
	v_mul_f32_e32 v131, 0xbfb8aa3b, v131
	v_mul_f32_e32 v200, v200, v201
	v_mul_f32_e32 v201, 0xbfb8aa3b, v201
	v_exp_f32_e32 v131, v131
	v_exp_f32_e32 v201, v201
	v_add_f32_e32 v131, 1.0, v131
	v_add_f32_e32 v201, 1.0, v201
	v_rcp_f32_e32 v131, v131
	v_rcp_f32_e32 v201, v201
	v_mul_f32_e32 v143, v130, v131
	v_mul_f32_e32 v0, v200, v201
	v_cvt_pk_bf16_f32 v130, v132, v135
	v_cvt_pk_bf16_f32 v131, v141, v143
	v_cvt_pk_bf16_f32 v132, v133, v140
	v_add_co_u32_e32 v140, vcc, s26, v136
	v_cvt_pk_bf16_f32 v133, v142, v0
	s_mov_b32 s26, 0x90000
	s_nop 0
	v_addc_co_u32_e32 v141, vcc, 0, v137, vcc
	global_store_dwordx4 v[140:141], v[130:133], off
	global_load_dword v0, v[138:139], off offset:576
	s_nop 0
	s_waitcnt vmcnt(0)
	v_mul_f32_e32 v130, v0, v46
	v_mul_f32_e32 v131, v0, v38
	v_mul_f32_e32 v200, v0, v42
	v_mul_f32_e32 v201, v0, v34
	v_mul_f32_e32 v130, v130, v131
	v_mul_f32_e32 v131, 0xbfb8aa3b, v131
	v_mul_f32_e32 v200, v200, v201
	v_mul_f32_e32 v201, 0xbfb8aa3b, v201
	v_exp_f32_e32 v131, v131
	v_exp_f32_e32 v201, v201
	v_add_f32_e32 v131, 1.0, v131
	v_add_f32_e32 v201, 1.0, v201
	v_rcp_f32_e32 v131, v131
	v_rcp_f32_e32 v201, v201
	v_mul_f32_e32 v132, v130, v131
	v_mul_f32_e32 v133, v200, v201
	v_mul_f32_e32 v130, v0, v47
	v_mul_f32_e32 v131, v0, v39
	v_mul_f32_e32 v200, v0, v43
	v_mul_f32_e32 v201, v0, v35
	v_mul_f32_e32 v130, v130, v131
	v_mul_f32_e32 v131, 0xbfb8aa3b, v131
	v_mul_f32_e32 v200, v200, v201
	v_mul_f32_e32 v201, 0xbfb8aa3b, v201
	v_exp_f32_e32 v131, v131
	v_exp_f32_e32 v201, v201
	v_add_f32_e32 v131, 1.0, v131
	v_add_f32_e32 v201, 1.0, v201
	v_rcp_f32_e32 v131, v131
	v_rcp_f32_e32 v201, v201
	v_mul_f32_e32 v135, v130, v131
	v_mul_f32_e32 v140, v200, v201
	v_mul_f32_e32 v130, v0, v48
	v_mul_f32_e32 v131, v0, v40
	v_mul_f32_e32 v200, v0, v44
	v_mul_f32_e32 v201, v0, v36
	v_mul_f32_e32 v130, v130, v131
	v_mul_f32_e32 v131, 0xbfb8aa3b, v131
	v_mul_f32_e32 v200, v200, v201
	v_mul_f32_e32 v201, 0xbfb8aa3b, v201
	v_exp_f32_e32 v131, v131
	v_exp_f32_e32 v201, v201
	v_add_f32_e32 v131, 1.0, v131
	v_add_f32_e32 v201, 1.0, v201
	v_rcp_f32_e32 v131, v131
	v_rcp_f32_e32 v201, v201
	v_mul_f32_e32 v141, v130, v131
	v_mul_f32_e32 v142, v200, v201
	v_mul_f32_e32 v130, v0, v49
	v_mul_f32_e32 v131, v0, v41
	v_mul_f32_e32 v200, v0, v45
	v_mul_f32_e32 v201, v0, v37
	v_mul_f32_e32 v130, v130, v131
	v_mul_f32_e32 v131, 0xbfb8aa3b, v131
	v_mul_f32_e32 v200, v200, v201
	v_mul_f32_e32 v201, 0xbfb8aa3b, v201
	v_exp_f32_e32 v131, v131
	v_exp_f32_e32 v201, v201
	v_add_f32_e32 v131, 1.0, v131
	v_add_f32_e32 v201, 1.0, v201
	v_rcp_f32_e32 v131, v131
	v_rcp_f32_e32 v201, v201
	v_mul_f32_e32 v143, v130, v131
	v_mul_f32_e32 v0, v200, v201
	v_cvt_pk_bf16_f32 v130, v132, v135
	v_cvt_pk_bf16_f32 v131, v141, v143
	v_cvt_pk_bf16_f32 v132, v133, v140
	v_add_co_u32_e32 v140, vcc, s26, v136
	v_cvt_pk_bf16_f32 v133, v142, v0
	s_mov_b32 s26, 0xa0000
	s_nop 0
	v_addc_co_u32_e32 v141, vcc, 0, v137, vcc
	global_store_dwordx4 v[140:141], v[130:133], off
	global_load_dword v0, v[138:139], off offset:640
	s_nop 0
	s_waitcnt vmcnt(0)
	v_mul_f32_e32 v130, v0, v30
	v_mul_f32_e32 v131, v0, v22
	v_mul_f32_e32 v200, v0, v26
	v_mul_f32_e32 v201, v0, v18
	v_mul_f32_e32 v130, v130, v131
	v_mul_f32_e32 v131, 0xbfb8aa3b, v131
	v_mul_f32_e32 v200, v200, v201
	v_mul_f32_e32 v201, 0xbfb8aa3b, v201
	v_exp_f32_e32 v131, v131
	v_exp_f32_e32 v201, v201
	v_add_f32_e32 v131, 1.0, v131
	v_add_f32_e32 v201, 1.0, v201
	v_rcp_f32_e32 v131, v131
	v_rcp_f32_e32 v201, v201
	v_mul_f32_e32 v132, v130, v131
	v_mul_f32_e32 v133, v200, v201
	v_mul_f32_e32 v130, v0, v31
	v_mul_f32_e32 v131, v0, v23
	v_mul_f32_e32 v200, v0, v27
	v_mul_f32_e32 v201, v0, v19
	v_mul_f32_e32 v130, v130, v131
	v_mul_f32_e32 v131, 0xbfb8aa3b, v131
	v_mul_f32_e32 v200, v200, v201
	v_mul_f32_e32 v201, 0xbfb8aa3b, v201
	v_exp_f32_e32 v131, v131
	v_exp_f32_e32 v201, v201
	v_add_f32_e32 v131, 1.0, v131
	v_add_f32_e32 v201, 1.0, v201
	v_rcp_f32_e32 v131, v131
	v_rcp_f32_e32 v201, v201
	v_mul_f32_e32 v135, v130, v131
	v_mul_f32_e32 v140, v200, v201
	v_mul_f32_e32 v130, v0, v32
	v_mul_f32_e32 v131, v0, v24
	v_mul_f32_e32 v200, v0, v28
	v_mul_f32_e32 v201, v0, v20
	v_mul_f32_e32 v130, v130, v131
	v_mul_f32_e32 v131, 0xbfb8aa3b, v131
	v_mul_f32_e32 v200, v200, v201
	v_mul_f32_e32 v201, 0xbfb8aa3b, v201
	v_exp_f32_e32 v131, v131
	v_exp_f32_e32 v201, v201
	v_add_f32_e32 v131, 1.0, v131
	v_add_f32_e32 v201, 1.0, v201
	v_rcp_f32_e32 v131, v131
	v_rcp_f32_e32 v201, v201
	v_mul_f32_e32 v141, v130, v131
	v_mul_f32_e32 v142, v200, v201
	v_mul_f32_e32 v130, v0, v33
	v_mul_f32_e32 v131, v0, v25
	v_mul_f32_e32 v200, v0, v29
	v_mul_f32_e32 v201, v0, v21
	v_mul_f32_e32 v130, v130, v131
	v_mul_f32_e32 v131, 0xbfb8aa3b, v131
	v_mul_f32_e32 v200, v200, v201
	v_mul_f32_e32 v201, 0xbfb8aa3b, v201
	v_exp_f32_e32 v131, v131
	v_exp_f32_e32 v201, v201
	v_add_f32_e32 v131, 1.0, v131
	v_add_f32_e32 v201, 1.0, v201
	v_rcp_f32_e32 v131, v131
	v_rcp_f32_e32 v201, v201
	v_mul_f32_e32 v143, v130, v131
	v_mul_f32_e32 v0, v200, v201
	v_cvt_pk_bf16_f32 v130, v132, v135
	v_cvt_pk_bf16_f32 v131, v141, v143
	v_cvt_pk_bf16_f32 v132, v133, v140
	v_add_co_u32_e32 v140, vcc, s26, v136
	v_cvt_pk_bf16_f32 v133, v142, v0
	s_nop 1
	v_addc_co_u32_e32 v141, vcc, 0, v137, vcc
	global_store_dwordx4 v[140:141], v[130:133], off
	global_load_dword v0, v[138:139], off offset:704
	v_add_co_u32_e32 v136, vcc, 0xb0000, v136
	v_addc_co_u32_e32 v137, vcc, 0, v137, vcc
	s_waitcnt vmcnt(0)
	v_mul_f32_e32 v130, v0, v14
	v_mul_f32_e32 v131, v0, v6
	v_mul_f32_e32 v200, v0, v10
	v_mul_f32_e32 v201, v0, v2
	v_mul_f32_e32 v130, v130, v131
	v_mul_f32_e32 v131, 0xbfb8aa3b, v131
	v_mul_f32_e32 v200, v200, v201
	v_mul_f32_e32 v201, 0xbfb8aa3b, v201
	v_exp_f32_e32 v131, v131
	v_exp_f32_e32 v201, v201
	v_add_f32_e32 v131, 1.0, v131
	v_add_f32_e32 v201, 1.0, v201
	v_rcp_f32_e32 v131, v131
	v_rcp_f32_e32 v201, v201
	v_mul_f32_e32 v132, v130, v131
	v_mul_f32_e32 v133, v200, v201
	v_mul_f32_e32 v130, v0, v15
	v_mul_f32_e32 v131, v0, v7
	v_mul_f32_e32 v200, v0, v11
	v_mul_f32_e32 v201, v0, v3
	v_mul_f32_e32 v130, v130, v131
	v_mul_f32_e32 v131, 0xbfb8aa3b, v131
	v_mul_f32_e32 v200, v200, v201
	v_mul_f32_e32 v201, 0xbfb8aa3b, v201
	v_exp_f32_e32 v131, v131
	v_exp_f32_e32 v201, v201
	v_add_f32_e32 v131, 1.0, v131
	v_add_f32_e32 v201, 1.0, v201
	v_rcp_f32_e32 v131, v131
	v_rcp_f32_e32 v201, v201
	v_mul_f32_e32 v135, v130, v131
	v_mul_f32_e32 v138, v200, v201
	v_mul_f32_e32 v130, v0, v16
	v_mul_f32_e32 v131, v0, v8
	v_mul_f32_e32 v200, v0, v12
	v_mul_f32_e32 v201, v0, v4
	v_mul_f32_e32 v130, v130, v131
	v_mul_f32_e32 v131, 0xbfb8aa3b, v131
	v_mul_f32_e32 v200, v200, v201
	v_mul_f32_e32 v201, 0xbfb8aa3b, v201
	v_exp_f32_e32 v131, v131
	v_exp_f32_e32 v201, v201
	v_add_f32_e32 v131, 1.0, v131
	v_add_f32_e32 v201, 1.0, v201
	v_rcp_f32_e32 v131, v131
	v_rcp_f32_e32 v201, v201
	v_mul_f32_e32 v139, v130, v131
	v_mul_f32_e32 v140, v200, v201
	v_mul_f32_e32 v130, v0, v17
	v_mul_f32_e32 v131, v0, v9
	v_mul_f32_e32 v200, v0, v13
	v_mul_f32_e32 v201, v0, v5
	v_mul_f32_e32 v130, v130, v131
	v_mul_f32_e32 v131, 0xbfb8aa3b, v131
	v_mul_f32_e32 v200, v200, v201
	v_mul_f32_e32 v201, 0xbfb8aa3b, v201
	v_exp_f32_e32 v131, v131
	v_exp_f32_e32 v201, v201
	v_add_f32_e32 v131, 1.0, v131
	v_add_f32_e32 v201, 1.0, v201
	v_rcp_f32_e32 v131, v131
	v_rcp_f32_e32 v201, v201
	v_mul_f32_e32 v141, v130, v131
	v_mul_f32_e32 v0, v200, v201
	v_cvt_pk_bf16_f32 v130, v132, v135
	v_cvt_pk_bf16_f32 v131, v139, v141
	v_cvt_pk_bf16_f32 v132, v133, v138
	v_cvt_pk_bf16_f32 v133, v140, v0
	global_store_dwordx4 v[136:137], v[130:133], off
